# v31: rwkv_mix row loop: 16 loop-invariant coefficient loads hoisted out of the loop; neighbour-row statistics and activation loads batched at the top of each row (6 dependent round trips -> ~2)
# speedup vs baseline: 1.0078x; 1.0078x over previous
; __device__ __forceinline__ void rwkv_mix(const bf16* HB, const float* ssq, const float* gain, const float* mu, bf16* P0, bf16* P1, int row0, int tid) {
;     const int lane = tid & 63, wave = tid >> 6; const int gw = blockIdx.x * 8 + wave, NGW = gridDim.x * 8;
;     for (int lr = gw; lr < SLAB; lr += NGW) {
;         const int r = row0 + lr; const bool pad = row_is_pad(r);
;         const float rs = rsqrtf(pg8::row_ssq16(ssq, r) * (1.0f / 1024.0f) + NEPS);
;         const float rsm = (r > 0) ? rsqrtf(pg8::row_ssq16(ssq, r - 1) * (1.0f / 1024.0f) + NEPS) : 0.f;
;         const float rsp = (r < TROWS - 1) ? rsqrtf(pg8::row_ssq16(ssq, r + 1) * (1.0f / 1024.0f) + NEPS) : 0.f;
; #pragma unroll
;         for (int h = 0; h < 2; ++h) { const int col = 16 * lane + 8 * h; const size_t off = (size_t)r * 1024 + col;
;             u32x4_t a = *(const u32x4_t*)(HB + off), am = (u32x4_t){0u, 0u, 0u, 0u}, ap = (u32x4_t){0u, 0u, 0u, 0u};
;             if (r > 0) am = *(const u32x4_t*)(HB + off - 1024);
;             if (r < TROWS - 1) ap = *(const u32x4_t*)(HB + off + 1024);
;             const unsigned aw[4] = {a.x, a.y, a.z, a.w}, mw[4] = {am.x, am.y, am.z, am.w}, pw[4] = {ap.x, ap.y, ap.z, ap.w};
;             float xr[8], xk[8], xv[8], xx[8];
;             const f32x4_t ga = *(const f32x4_t*)(gain + col), gb = *(const f32x4_t*)(gain + col + 4);
;             const f32x4_t ra = *(const f32x4_t*)(mu + col), rb = *(const f32x4_t*)(mu + col + 4), ka = *(const f32x4_t*)(mu + 2048 + col), kb = *(const f32x4_t*)(mu + 2048 + col + 4), va = *(const f32x4_t*)(mu + 3072 + col), vb = *(const f32x4_t*)(mu + 3072 + col + 4);
.LBB0_364:
	s_and_b64 vcc, exec, s[0:1]
	s_cbranch_vccz .LBB0_388
	v_ashrrev_i32_e32 v0, 6, v202
	s_waitcnt vmcnt(0)
	v_add_u32_e32 v32, s93, v0
	s_movk_i32 s0, 0x4100
	v_cmp_gt_i32_e32 vcc, s0, v32
	s_and_saveexec_b64 s[0:1], vcc
	s_cbranch_execz .LBB0_497
	v_readlane_b32 s12, v255, 5
	v_readlane_b32 s13, v255, 6
	s_load_dwordx2 s[10:11], s[12:13], 0x18
	s_add_u32 s8, s6, 0x520000
	s_load_dwordx2 s[12:13], s[12:13], 0x50
	s_addc_u32 s9, s7, 0
	v_lshlrev_b32_e32 v0, 6, v203
	s_waitcnt lgkmcnt(0)
	s_add_u32 s10, s10, 0x1000
	s_addc_u32 s11, s11, 0
	s_add_u32 s18, s12, 0x2000
	s_addc_u32 s19, s13, 0
	s_add_u32 s20, s12, 0x3000
	s_addc_u32 s21, s13, 0
	v_and_b32_e32 v0, 0xfc0, v0
	s_mul_i32 s2, s40, 0x4100
	v_lshl_add_u64 v[34:35], s[10:11], 0, v[0:1]
	v_lshl_add_u64 v[36:37], s[12:13], 0, v[0:1]
	v_lshl_add_u64 v[38:39], s[18:19], 0, v[0:1]
	v_lshl_add_u64 v[40:41], s[20:21], 0, v[0:1]
	v_or_b32_e32 v0, 32, v0
	v_add_u32_e32 v2, s2, v32
	v_lshl_add_u64 v[42:43], s[10:11], 0, v[0:1]
	v_lshl_add_u64 v[44:45], s[18:19], 0, v[0:1]
	v_lshl_add_u64 v[46:47], s[20:21], 0, v[0:1]
	v_lshlrev_b32_e32 v0, 5, v203
	v_ashrrev_i32_e32 v3, 31, v2
	v_and_b32_e32 v0, 0x7e0, v0
	v_lshlrev_b64 v[50:51], 6, v[2:3]
	v_lshlrev_b64 v[2:3], 11, v[2:3]
	v_ashrrev_i32_e32 v33, 31, v32
	v_or_b32_e32 v2, v2, v0
	v_lshlrev_b64 v[48:49], 12, v[32:33]
	v_lshl_add_u64 v[2:3], s[4:5], 0, v[2:3]
	v_or_b32_e32 v48, v48, v0
	v_lshl_add_u64 v[52:53], v[2:3], 0, 16
	s_mov_b64 s[10:11], 0
	global_load_dwordx4 v[100:103], v[42:43], off offset:16
	global_load_dwordx4 v[104:107], v[42:43], off
	global_load_dwordx4 v[108:111], v[36:37], off offset:48
	global_load_dwordx4 v[112:115], v[36:37], off offset:32
	global_load_dwordx4 v[116:119], v[44:45], off offset:16
	global_load_dwordx4 v[120:123], v[44:45], off
	global_load_dwordx4 v[124:127], v[46:47], off offset:16
	global_load_dwordx4 v[128:131], v[46:47], off
	global_load_dwordx4 v[132:135], v[34:35], off offset:16
	global_load_dwordx4 v[136:139], v[34:35], off
	global_load_dwordx4 v[140:143], v[36:37], off offset:16
	global_load_dwordx4 v[144:147], v[36:37], off
	global_load_dwordx4 v[148:151], v[38:39], off offset:16
	global_load_dwordx4 v[152:155], v[38:39], off
	global_load_dwordx4 v[156:159], v[40:41], off offset:16
	global_load_dwordx4 v[160:163], v[40:41], off
	s_waitcnt vmcnt(0)
	s_branch .LBB0_368
; __device__ __forceinline__ void rwkv_mix(const bf16* HB, const float* ssq, const float* gain, const float* mu, bf16* P0, bf16* P1, int row0, int tid) {
;     ...
;         for (int h = 0; h < 2; ++h) { const int col = 16 * lane + 8 * h; const size_t off = (size_t)r * 1024 + col;
;             u32x4_t a = *(const u32x4_t*)(HB + off), am = (u32x4_t){0u, 0u, 0u, 0u}, ap = (u32x4_t){0u, 0u, 0u, 0u};
;             if (r > 0) am = *(const u32x4_t*)(HB + off - 1024);
;             if (r < TROWS - 1) ap = *(const u32x4_t*)(HB + off + 1024);
;             const unsigned aw[4] = {a.x, a.y, a.z, a.w}, mw[4] = {am.x, am.y, am.z, am.w}, pw[4] = {ap.x, ap.y, ap.z, ap.w};
;             float xr[8], xk[8], xv[8], xx[8];
;             const f32x4_t ga = *(const f32x4_t*)(gain + col), gb = *(const f32x4_t*)(gain + col + 4);
;             const f32x4_t ra = *(const f32x4_t*)(mu + col), rb = *(const f32x4_t*)(mu + col + 4), ka = *(const f32x4_t*)(mu + 2048 + col), kb = *(const f32x4_t*)(mu + 2048 + col + 4), va = *(const f32x4_t*)(mu + 3072 + col), vb = *(const f32x4_t*)(mu + 3072 + col + 4);
;             const float keep = pad ? 0.f : 1.f;
; #pragma unroll
;             for (int q = 0; q < 4; ++q) {
; #pragma unroll
;                 for (int hh = 0; hh < 2; ++hh) { const int i8 = 2 * q + hh; const float g0 = (i8 < 4 ? ga[i8 & 3] : gb[i8 & 3]) * keep;
;                     const float mr = i8 < 4 ? ra[i8 & 3] : rb[i8 & 3], mk = i8 < 4 ? ka[i8 & 3] : kb[i8 & 3], mv = i8 < 4 ? va[i8 & 3] : vb[i8 & 3];
;                     const float x0 = (hh ? __uint_as_float(aw[q] & 0xffff0000u) : __uint_as_float(aw[q] << 16)) * rs * g0;
;                     const float m0 = (hh ? __uint_as_float(mw[q] & 0xffff0000u) : __uint_as_float(mw[q] << 16)) * rsm * g0;
;                     const float p0 = (hh ? __uint_as_float(pw[q] & 0xffff0000u) : __uint_as_float(pw[q] << 16)) * rsp * g0;
;                     const float d0 = 0.5f * (m0 + p0) - x0;
;                     xx[i8] = d0; xr[i8] = x0 + d0 * mr; xk[i8] = x0 + d0 * mk; xv[i8] = x0 + d0 * mv; } }
;             u32x4_t w; w.x = pk2(xr[0], xr[1]); w.y = pk2(xr[2], xr[3]); w.z = pk2(xr[4], xr[5]); w.w = pk2(xr[6], xr[7]);
;             *(u32x4_t*)(P0 + (size_t)lr * 2048 + col) = w;
;             w.x = pk2(xx[0], xx[1]); w.y = pk2(xx[2], xx[3]); w.z = pk2(xx[4], xx[5]); w.w = pk2(xx[6], xx[7]);
.LBB0_367:
	s_or_b64 exec, exec, s[12:13]
	v_mov_b64_e32 v[26:27], v[100:101]
	v_mov_b64_e32 v[28:29], v[102:103]
	v_mov_b64_e32 v[70:71], v[104:105]
	v_mov_b64_e32 v[72:73], v[106:107]
	v_mov_b64_e32 v[10:11], v[108:109]
	v_mov_b64_e32 v[12:13], v[110:111]
	v_mov_b64_e32 v[74:75], v[112:113]
	v_mov_b64_e32 v[76:77], v[114:115]
	v_mov_b64_e32 v[6:7], v[116:117]
	v_mov_b64_e32 v[8:9], v[118:119]
	v_mov_b64_e32 v[78:79], v[120:121]
	v_mov_b64_e32 v[80:81], v[122:123]
	v_mov_b64_e32 v[14:15], v[124:125]
	v_mov_b64_e32 v[16:17], v[126:127]
	v_mov_b64_e32 v[82:83], v[128:129]
	v_mov_b64_e32 v[84:85], v[130:131]
	v_mov_b32_e32 v57, v56
	v_mov_b32_e32 v59, v58
	v_mov_b32_e32 v61, v60
	v_mov_b32_e32 v55, v54
	s_waitcnt vmcnt(0)
	v_lshlrev_b32_e32 v66, 16, v18
	v_and_b32_e32 v67, 0xffff0000, v18
	v_lshlrev_b32_e32 v68, 16, v2
	v_and_b32_e32 v69, 0xffff0000, v2
	v_pk_mul_f32 v[66:67], v[60:61], v[66:67]
	v_pk_mul_f32 v[68:69], v[54:55], v[68:69]
	v_lshlrev_b32_e32 v18, 16, v19
	v_and_b32_e32 v19, 0xffff0000, v19
	v_lshlrev_b32_e32 v2, 16, v3
	v_and_b32_e32 v3, 0xffff0000, v3
	v_pk_mul_f32 v[18:19], v[60:61], v[18:19]
	v_pk_mul_f32 v[2:3], v[54:55], v[2:3]
	v_readlane_b32 s12, v254, 44
	v_readlane_b32 s13, v254, 45
	v_add_u32_e32 v32, s80, v32
	v_cmp_lt_i32_e32 vcc, s82, v32
	v_lshl_add_u64 v[48:49], v[48:49], 0, s[12:13]
	v_readlane_b32 s12, v254, 40
	v_readlane_b32 s13, v254, 41
	s_or_b64 s[10:11], vcc, s[10:11]
	s_nop 0
	v_pk_mul_f32 v[26:27], v[56:57], v[26:27]
	s_nop 0
	v_pk_mul_f32 v[64:65], v[56:57], v[70:71]
	v_lshlrev_b32_e32 v70, 16, v22
	v_and_b32_e32 v71, 0xffff0000, v22
	v_pk_mul_f32 v[70:71], v[58:59], v[70:71]
	v_lshlrev_b32_e32 v22, 16, v23
	v_and_b32_e32 v23, 0xffff0000, v23
	v_pk_mul_f32 v[70:71], v[64:65], v[70:71]
	v_pk_mul_f32 v[72:73], v[56:57], v[72:73]
	v_pk_mul_f32 v[22:23], v[58:59], v[22:23]
	v_pk_mul_f32 v[66:67], v[66:67], v[64:65]
	v_pk_fma_f32 v[64:65], v[68:69], v[64:65], v[70:71]
	v_pk_mul_f32 v[22:23], v[72:73], v[22:23]
	v_pk_fma_f32 v[68:69], v[64:65], 0.5, v[66:67] op_sel_hi:[1,0,1] neg_lo:[0,0,1] neg_hi:[0,0,1]
	v_pk_mul_f32 v[18:19], v[18:19], v[72:73]
	v_pk_fma_f32 v[2:3], v[2:3], v[72:73], v[22:23]
	s_nop 0
	v_pk_fma_f32 v[64:65], v[82:83], v[68:69], v[66:67]
	v_pk_fma_f32 v[70:71], v[74:75], v[68:69], v[66:67]
	v_pk_fma_f32 v[66:67], v[78:79], v[68:69], v[66:67]
	v_pk_fma_f32 v[22:23], v[2:3], 0.5, v[18:19] op_sel_hi:[1,0,1] neg_lo:[0,0,1] neg_hi:[0,0,1]
	v_lshlrev_b32_e32 v78, 16, v24
	v_and_b32_e32 v79, 0xffff0000, v24
	v_lshlrev_b32_e32 v24, 16, v25
	v_and_b32_e32 v25, 0xffff0000, v25
	v_pk_fma_f32 v[72:73], v[76:77], v[22:23], v[18:19]
	v_lshlrev_b32_e32 v74, 16, v20
	v_and_b32_e32 v75, 0xffff0000, v20
	v_lshlrev_b32_e32 v76, 16, v4
	v_and_b32_e32 v77, 0xffff0000, v4
	v_pk_mul_f32 v[78:79], v[58:59], v[78:79]
	v_pk_mul_f32 v[28:29], v[56:57], v[28:29]
	v_lshlrev_b32_e32 v20, 16, v21
	v_and_b32_e32 v21, 0xffff0000, v21
	v_lshlrev_b32_e32 v4, 16, v5
	v_and_b32_e32 v5, 0xffff0000, v5
	v_pk_mul_f32 v[24:25], v[58:59], v[24:25]
	v_pk_mul_f32 v[74:75], v[60:61], v[74:75]
	v_pk_mul_f32 v[76:77], v[54:55], v[76:77]
	v_pk_mul_f32 v[78:79], v[26:27], v[78:79]
	v_pk_mul_f32 v[20:21], v[60:61], v[20:21]
	v_pk_mul_f32 v[4:5], v[54:55], v[4:5]
	v_pk_mul_f32 v[24:25], v[28:29], v[24:25]
	v_pk_mul_f32 v[74:75], v[74:75], v[26:27]
	v_pk_fma_f32 v[26:27], v[76:77], v[26:27], v[78:79]
	v_pk_mul_f32 v[20:21], v[20:21], v[28:29]
	v_pk_fma_f32 v[4:5], v[4:5], v[28:29], v[24:25]
	v_pk_fma_f32 v[26:27], v[26:27], 0.5, v[74:75] op_sel_hi:[1,0,1] neg_lo:[0,0,1] neg_hi:[0,0,1]
	v_pk_fma_f32 v[4:5], v[4:5], 0.5, v[20:21] op_sel_hi:[1,0,1] neg_lo:[0,0,1] neg_hi:[0,0,1]
	v_pk_fma_f32 v[10:11], v[10:11], v[26:27], v[74:75]
	v_pk_fma_f32 v[12:13], v[12:13], v[4:5], v[20:21]
	v_pk_fma_f32 v[2:3], v[84:85], v[22:23], v[18:19]
	v_pk_fma_f32 v[18:19], v[80:81], v[22:23], v[18:19]
	v_pk_fma_f32 v[6:7], v[6:7], v[26:27], v[74:75]
	v_pk_fma_f32 v[16:17], v[4:5], v[16:17], v[20:21]
	v_pk_fma_f32 v[20:21], v[8:9], v[4:5], v[20:21]
	v_cvt_pk_bf16_f32 v8, v70, v71
	v_cvt_pk_bf16_f32 v9, v72, v73
	v_cvt_pk_bf16_f32 v10, v10, v11
	v_cvt_pk_bf16_f32 v11, v12, v13
	v_lshl_add_u64 v[50:51], v[50:51], 0, s[12:13]
	v_readlane_b32 s12, v254, 42
	v_pk_fma_f32 v[14:15], v[26:27], v[14:15], v[74:75]
	global_store_dwordx4 v[30:31], v[8:11], off offset:16
	v_cvt_pk_bf16_f32 v6, v6, v7
	v_cvt_pk_bf16_f32 v7, v20, v21
	v_cvt_pk_bf16_f32 v11, v4, v5
	v_cvt_pk_bf16_f32 v4, v66, v67
	v_cvt_pk_bf16_f32 v5, v18, v19
	v_readlane_b32 s13, v254, 43
	v_cvt_pk_bf16_f32 v8, v68, v69
	v_cvt_pk_bf16_f32 v9, v22, v23
	v_cvt_pk_bf16_f32 v10, v26, v27
	global_store_dwordx4 v[62:63], v[4:7], off offset:16
	v_lshl_add_u64 v[52:53], v[52:53], 0, s[12:13]
	global_store_dwordx4 v[30:31], v[8:11], off offset:2064
	v_cvt_pk_bf16_f32 v4, v64, v65
	v_cvt_pk_bf16_f32 v5, v2, v3
	v_cvt_pk_bf16_f32 v6, v14, v15
	v_cvt_pk_bf16_f32 v7, v16, v17
	global_store_dwordx4 v[62:63], v[4:7], off offset:2064
	s_andn2_b64 exec, exec, s[10:11]
	s_cbranch_execz .LBB0_497

; __device__ __forceinline__ void rwkv_mix(const bf16* HB, const float* ssq, const float* gain, const float* mu, bf16* P0, bf16* P1, int row0, int tid) {
;     ...
;         const int r = row0 + lr; const bool pad = row_is_pad(r);
;         const float rs = rsqrtf(pg8::row_ssq16(ssq, r) * (1.0f / 1024.0f) + NEPS);
;         const float rsm = (r > 0) ? rsqrtf(pg8::row_ssq16(ssq, r - 1) * (1.0f / 1024.0f) + NEPS) : 0.f;
;         const float rsp = (r < TROWS - 1) ? rsqrtf(pg8::row_ssq16(ssq, r + 1) * (1.0f / 1024.0f) + NEPS) : 0.f;
; #pragma unroll
;         for (int h = 0; h < 2; ++h) { const int col = 16 * lane + 8 * h; const size_t off = (size_t)r * 1024 + col;
;             u32x4_t a = *(const u32x4_t*)(HB + off), am = (u32x4_t){0u, 0u, 0u, 0u}, ap = (u32x4_t){0u, 0u, 0u, 0u};
;             if (r > 0) am = *(const u32x4_t*)(HB + off - 1024);
;             if (r < TROWS - 1) ap = *(const u32x4_t*)(HB + off + 1024);
;             const unsigned aw[4] = {a.x, a.y, a.z, a.w}, mw[4] = {am.x, am.y, am.z, am.w}, pw[4] = {ap.x, ap.y, ap.z, ap.w};
.LBB0_374:
	s_or_b64 exec, exec, s[12:13]
	v_mov_b32_e32 v54, 0
	v_mov_b32_e32 v56, 0
	s_and_saveexec_b64 s[12:13], s[18:19]
	v_cmp_gt_i32_e32 vcc, 48, v0
	s_nop 1
	v_cndmask_b32_e64 v56, 1.0, 0, vcc
	s_or_b64 exec, exec, s[12:13]
	v_lshl_add_u64 v[4:5], s[6:7], 0, v[50:51]
	s_mov_b64 s[12:13], 0x520000
	v_lshl_add_u64 v[6:7], v[4:5], 0, s[12:13]
	v_add_co_u32_e32 v4, vcc, 0x520000, v4
	v_cmp_lt_i32_e64 s[36:37], 0, v2
	s_nop 0
	v_addc_co_u32_e32 v5, vcc, 0, v5, vcc
	global_load_dwordx4 v[24:27], v[4:5], off
	global_load_dwordx4 v[16:19], v[6:7], off offset:48
	global_load_dwordx4 v[28:31], v[6:7], off offset:32
	global_load_dwordx4 v[20:23], v[6:7], off offset:16
	s_mov_b32 s2, 0x81ff
	v_cmp_gt_i32_e64 s[38:39], s2, v2
	s_and_saveexec_b64 s[12:13], s[36:37]
	v_add_u32_e32 v98, -1, v2
	v_mov_b32_e32 v99, v1
	v_lshlrev_b64 v[98:99], 6, v[98:99]
	v_lshl_add_u64 v[98:99], s[8:9], 0, v[98:99]
	global_load_dwordx4 v[164:167], v[98:99], off
	global_load_dwordx4 v[168:171], v[98:99], off offset:32
	global_load_dwordx4 v[172:175], v[98:99], off offset:16
	global_load_dwordx4 v[176:179], v[98:99], off offset:48
	s_or_b64 exec, exec, s[12:13]
	s_and_saveexec_b64 s[12:13], s[38:39]
	v_add_u32_e32 v98, 1, v2
	v_ashrrev_i32_e32 v99, 31, v98
	v_lshlrev_b64 v[98:99], 6, v[98:99]
	v_lshl_add_u64 v[98:99], s[8:9], 0, v[98:99]
	global_load_dwordx4 v[180:183], v[98:99], off
	global_load_dwordx4 v[184:187], v[98:99], off offset:32
	global_load_dwordx4 v[188:191], v[98:99], off offset:16
	global_load_dwordx4 v[192:195], v[98:99], off offset:48
	s_or_b64 exec, exec, s[12:13]
	global_load_dwordx4 v[86:89], v[52:53], off offset:-16
	s_and_saveexec_b64 s[12:13], s[36:37]
	global_load_dwordx4 v[90:93], v[52:53], off offset:-2064
	s_or_b64 exec, exec, s[12:13]
	s_and_saveexec_b64 s[12:13], s[38:39]
	global_load_dwordx4 v[94:97], v[52:53], off offset:2032
	s_or_b64 exec, exec, s[12:13]
	s_waitcnt vmcnt(0)
	s_and_saveexec_b64 s[12:13], s[36:37]
	s_cbranch_execz .LBB0_378
	v_add_u32_e32 v0, -1, v2
	v_lshlrev_b64 v[4:5], 6, v[0:1]
	v_lshl_add_u64 v[54:55], s[8:9], 0, v[4:5]
	v_mov_b64_e32 v[4:5], v[164:165]
	v_mov_b64_e32 v[6:7], v[166:167]
	v_mov_b64_e32 v[8:9], v[168:169]
	v_mov_b64_e32 v[10:11], v[170:171]
	v_mov_b64_e32 v[12:13], v[172:173]
	v_mov_b64_e32 v[14:15], v[174:175]
	v_mov_b64_e32 v[58:59], v[176:177]
	v_mov_b64_e32 v[60:61], v[178:179]
	s_waitcnt vmcnt(0)
	v_mov_b32_e32 v54, v4
	v_mov_b32_e32 v55, v8
	v_mov_b32_e32 v8, v5
	v_mov_b32_e32 v4, v6
	v_mov_b32_e32 v5, v10
	v_mov_b32_e32 v10, v7
	v_mov_b32_e32 v6, v12
	v_mov_b32_e32 v7, v58
	v_mov_b32_e32 v58, v13
	v_mov_b32_e32 v12, v14
	v_mov_b32_e32 v13, v60
	v_mov_b32_e32 v60, v15
	v_pk_add_f32 v[8:9], v[54:55], v[8:9]
	v_pk_add_f32 v[4:5], v[4:5], v[10:11]
	v_pk_add_f32 v[6:7], v[6:7], v[58:59]
	v_pk_add_f32 v[10:11], v[12:13], v[60:61]
	v_pk_add_f32 v[4:5], v[8:9], v[4:5]
	v_pk_add_f32 v[6:7], v[6:7], v[10:11]
	s_nop 0
	v_pk_add_f32 v[4:5], v[4:5], v[6:7]
	s_nop 0
	v_add_f32_e32 v0, v4, v5
	v_fmamk_f32 v0, v0, 0x3a800000, v196
	v_mul_f32_e32 v3, 0x4b800000, v0
	v_cmp_gt_f32_e32 vcc, s33, v0
	s_nop 1
	v_cndmask_b32_e32 v0, v0, v3, vcc
	v_rsq_f32_e32 v0, v0
	s_nop 0
	v_mul_f32_e32 v3, 0x45800000, v0
	v_cndmask_b32_e32 v54, v0, v3, vcc
.LBB0_378:
	s_or_b64 exec, exec, s[12:13]
	s_mov_b32 s2, 0x81ff
	v_cmp_gt_i32_e64 s[38:39], s2, v2
	v_mov_b32_e32 v4, 0
	v_mov_b32_e32 v58, 0
	s_and_saveexec_b64 s[12:13], s[38:39]
	s_cbranch_execz .LBB0_380
	v_add_u32_e32 v2, 1, v2
	v_ashrrev_i32_e32 v3, 31, v2
	v_lshlrev_b64 v[2:3], 6, v[2:3]
	v_lshl_add_u64 v[2:3], s[8:9], 0, v[2:3]
	v_mov_b64_e32 v[6:7], v[180:181]
	v_mov_b64_e32 v[8:9], v[182:183]
	v_mov_b64_e32 v[10:11], v[184:185]
	v_mov_b64_e32 v[12:13], v[186:187]
	v_mov_b64_e32 v[58:59], v[188:189]
	v_mov_b64_e32 v[60:61], v[190:191]
	v_mov_b64_e32 v[62:63], v[192:193]
	v_mov_b64_e32 v[64:65], v[194:195]
	s_waitcnt vmcnt(0)
	v_mov_b32_e32 v2, v6
	v_mov_b32_e32 v3, v10
	v_mov_b32_e32 v10, v7
	v_mov_b32_e32 v6, v8
	v_mov_b32_e32 v7, v12
	v_mov_b32_e32 v12, v9
	v_mov_b32_e32 v8, v58
	v_mov_b32_e32 v9, v62
	v_mov_b32_e32 v62, v59
	v_mov_b32_e32 v14, v60
	v_mov_b32_e32 v15, v64
	v_mov_b32_e32 v64, v61
	v_pk_add_f32 v[2:3], v[2:3], v[10:11]
	v_pk_add_f32 v[6:7], v[6:7], v[12:13]
	v_pk_add_f32 v[8:9], v[8:9], v[62:63]
	v_pk_add_f32 v[10:11], v[14:15], v[64:65]
	v_pk_add_f32 v[2:3], v[2:3], v[6:7]
	v_pk_add_f32 v[6:7], v[8:9], v[10:11]
	s_nop 0
	v_pk_add_f32 v[2:3], v[2:3], v[6:7]
	s_nop 0
	v_add_f32_e32 v0, v2, v3
	v_fmamk_f32 v0, v0, 0x3a800000, v196
	v_mul_f32_e32 v2, 0x4b800000, v0
	v_cmp_gt_f32_e32 vcc, s33, v0
	s_nop 1
	v_cndmask_b32_e32 v0, v0, v2, vcc
	v_rsq_f32_e32 v0, v0
	s_nop 0
	v_mul_f32_e32 v2, 0x45800000, v0
	v_cndmask_b32_e32 v58, v0, v2, vcc
.LBB0_380:
	s_or_b64 exec, exec, s[12:13]
	v_mov_b64_e32 v[8:9], v[86:87]
	v_mov_b64_e32 v[10:11], v[88:89]
	v_mov_b32_e32 v5, 0
	v_mov_b32_e32 v6, 0
	v_mov_b32_e32 v7, 0
	s_and_saveexec_b64 s[12:13], s[36:37]
	s_cbranch_execz .LBB0_382
	v_mov_b64_e32 v[4:5], v[90:91]
	v_mov_b64_e32 v[6:7], v[92:93]
.LBB0_382:
	s_or_b64 exec, exec, s[12:13]
	v_mov_b32_e32 v2, 0
	v_mov_b32_e32 v12, 0
	v_mov_b32_e32 v13, 0
	v_mov_b32_e32 v14, 0
	v_mov_b32_e32 v15, 0
	s_and_saveexec_b64 s[12:13], s[38:39]
	s_cbranch_execz .LBB0_384
	v_mov_b64_e32 v[12:13], v[94:95]
	v_mov_b64_e32 v[14:15], v[96:97]
; __device__ __forceinline__ void rwkv_mix(const bf16* HB, const float* ssq, const float* gain, const float* mu, bf16* P0, bf16* P1, int row0, int tid) {
;     ...
;         const float rs = rsqrtf(pg8::row_ssq16(ssq, r) * (1.0f / 1024.0f) + NEPS);
;         const float rsm = (r > 0) ? rsqrtf(pg8::row_ssq16(ssq, r - 1) * (1.0f / 1024.0f) + NEPS) : 0.f;
;         const float rsp = (r < TROWS - 1) ? rsqrtf(pg8::row_ssq16(ssq, r + 1) * (1.0f / 1024.0f) + NEPS) : 0.f;
; #pragma unroll
;         for (int h = 0; h < 2; ++h) { const int col = 16 * lane + 8 * h; const size_t off = (size_t)r * 1024 + col;
;             u32x4_t a = *(const u32x4_t*)(HB + off), am = (u32x4_t){0u, 0u, 0u, 0u}, ap = (u32x4_t){0u, 0u, 0u, 0u};
;             if (r > 0) am = *(const u32x4_t*)(HB + off - 1024);
;             if (r < TROWS - 1) ap = *(const u32x4_t*)(HB + off + 1024);
;             const unsigned aw[4] = {a.x, a.y, a.z, a.w}, mw[4] = {am.x, am.y, am.z, am.w}, pw[4] = {ap.x, ap.y, ap.z, ap.w};
;             float xr[8], xk[8], xv[8], xx[8];
;             const f32x4_t ga = *(const f32x4_t*)(gain + col), gb = *(const f32x4_t*)(gain + col + 4);
;             const f32x4_t ra = *(const f32x4_t*)(mu + col), rb = *(const f32x4_t*)(mu + col + 4), ka = *(const f32x4_t*)(mu + 2048 + col), kb = *(const f32x4_t*)(mu + 2048 + col + 4), va = *(const f32x4_t*)(mu + 3072 + col), vb = *(const f32x4_t*)(mu + 3072 + col + 4);
;             const float keep = pad ? 0.f : 1.f;
; #pragma unroll
;             for (int q = 0; q < 4; ++q) {
; #pragma unroll
;                 for (int hh = 0; hh < 2; ++hh) { const int i8 = 2 * q + hh; const float g0 = (i8 < 4 ? ga[i8 & 3] : gb[i8 & 3]) * keep;
;                     const float mr = i8 < 4 ? ra[i8 & 3] : rb[i8 & 3], mk = i8 < 4 ? ka[i8 & 3] : kb[i8 & 3], mv = i8 < 4 ? va[i8 & 3] : vb[i8 & 3];
;                     const float x0 = (hh ? __uint_as_float(aw[q] & 0xffff0000u) : __uint_as_float(aw[q] << 16)) * rs * g0;
;                     const float m0 = (hh ? __uint_as_float(mw[q] & 0xffff0000u) : __uint_as_float(mw[q] << 16)) * rsm * g0;
;                     const float p0 = (hh ? __uint_as_float(pw[q] & 0xffff0000u) : __uint_as_float(pw[q] << 16)) * rsp * g0;
;                     const float d0 = 0.5f * (m0 + p0) - x0;
;                     xx[i8] = d0; xr[i8] = x0 + d0 * mr; xk[i8] = x0 + d0 * mk; xv[i8] = x0 + d0 * mv; } }
.LBB0_384:
	s_or_b64 exec, exec, s[12:13]
	s_waitcnt vmcnt(0)
	v_mov_b32_e32 v60, v24
	v_mov_b32_e32 v61, v28
	v_mov_b32_e32 v28, v25
	v_pk_add_f32 v[24:25], v[60:61], v[28:29]
	v_mov_b32_e32 v28, v26
	v_mov_b32_e32 v29, v30
	v_mov_b32_e32 v30, v27
	v_pk_add_f32 v[26:27], v[28:29], v[30:31]
	v_lshlrev_b32_e32 v64, 16, v8
	v_pk_add_f32 v[24:25], v[24:25], v[26:27]
	v_mov_b32_e32 v26, v20
	v_mov_b32_e32 v27, v16
	v_mov_b32_e32 v16, v21
	v_mov_b32_e32 v20, v22
	v_mov_b32_e32 v21, v18
	v_mov_b32_e32 v18, v23
	v_pk_add_f32 v[16:17], v[26:27], v[16:17]
	v_pk_add_f32 v[18:19], v[20:21], v[18:19]
	v_and_b32_e32 v65, 0xffff0000, v8
	v_pk_add_f32 v[16:17], v[16:17], v[18:19]
	v_lshlrev_b32_e32 v66, 16, v12
	v_pk_add_f32 v[16:17], v[24:25], v[16:17]
	v_and_b32_e32 v67, 0xffff0000, v12
	v_add_f32_e32 v0, v16, v17
	v_mov_b64_e32 v[16:17], v[132:133]
	v_mov_b64_e32 v[18:19], v[134:135]
	v_mov_b64_e32 v[68:69], v[136:137]
	v_mov_b64_e32 v[70:71], v[138:139]
	v_mov_b64_e32 v[24:25], v[140:141]
	v_mov_b64_e32 v[26:27], v[142:143]
	v_mov_b64_e32 v[72:73], v[144:145]
	v_mov_b64_e32 v[74:75], v[146:147]
	v_mov_b64_e32 v[20:21], v[148:149]
	v_mov_b64_e32 v[22:23], v[150:151]
	v_mov_b64_e32 v[76:77], v[152:153]
	v_mov_b64_e32 v[78:79], v[154:155]
	v_mov_b64_e32 v[28:29], v[156:157]
	v_mov_b64_e32 v[30:31], v[158:159]
	v_mov_b64_e32 v[80:81], v[160:161]
	v_mov_b64_e32 v[82:83], v[162:163]
	v_fmamk_f32 v0, v0, 0x3a800000, v196
	v_cmp_gt_f32_e32 vcc, s33, v0
	v_mul_f32_e32 v3, 0x4b800000, v0
	v_pk_mul_f32 v[66:67], v[58:59], v[66:67] op_sel_hi:[0,1]
	v_cndmask_b32_e32 v0, v0, v3, vcc
	v_rsq_f32_e32 v0, v0
	v_lshlrev_b32_e32 v12, 16, v13
	v_and_b32_e32 v13, 0xffff0000, v13
	v_lshlrev_b32_e32 v8, 16, v9
	v_mul_f32_e32 v3, 0x45800000, v0
	v_cndmask_b32_e32 v60, v0, v3, vcc
	v_pk_mul_f32 v[64:65], v[60:61], v[64:65] op_sel_hi:[0,1]
	v_and_b32_e32 v9, 0xffff0000, v9
	v_pk_mul_f32 v[12:13], v[58:59], v[12:13] op_sel_hi:[0,1]
	v_pk_mul_f32 v[8:9], v[60:61], v[8:9] op_sel_hi:[0,1]
	s_mov_b32 s2, 0x1800000
	v_mov_b32_e32 v3, 0
	s_nop 0
	v_pk_mul_f32 v[16:17], v[56:57], v[16:17] op_sel_hi:[0,1]
	s_nop 0
	v_pk_mul_f32 v[62:63], v[56:57], v[68:69] op_sel_hi:[0,1]
	v_pk_mul_f32 v[84:85], v[64:65], v[62:63]
	v_lshlrev_b32_e32 v64, 16, v4
	v_and_b32_e32 v65, 0xffff0000, v4
	v_pk_mul_f32 v[64:65], v[54:55], v[64:65] op_sel_hi:[0,1]
	v_pk_mul_f32 v[66:67], v[62:63], v[66:67]
	v_pk_mul_f32 v[70:71], v[56:57], v[70:71] op_sel_hi:[0,1]
	v_lshlrev_b32_e32 v4, 16, v5
	v_and_b32_e32 v5, 0xffff0000, v5
	v_pk_fma_f32 v[62:63], v[64:65], v[62:63], v[66:67]
	v_pk_mul_f32 v[4:5], v[54:55], v[4:5] op_sel_hi:[0,1]
	v_pk_mul_f32 v[12:13], v[70:71], v[12:13]
	v_pk_fma_f32 v[66:67], v[62:63], 0.5, v[84:85] op_sel_hi:[1,0,1] neg_lo:[0,0,1] neg_hi:[0,0,1]
	v_pk_mul_f32 v[8:9], v[8:9], v[70:71]
	v_pk_fma_f32 v[4:5], v[4:5], v[70:71], v[12:13]
	s_nop 0
	v_pk_fma_f32 v[62:63], v[76:77], v[66:67], v[84:85]
	v_pk_fma_f32 v[12:13], v[4:5], 0.5, v[8:9] op_sel_hi:[1,0,1] neg_lo:[0,0,1] neg_hi:[0,0,1]
	v_lshlrev_b32_e32 v76, 16, v14
	v_and_b32_e32 v77, 0xffff0000, v14
	v_lshlrev_b32_e32 v14, 16, v15
	v_and_b32_e32 v15, 0xffff0000, v15
	v_pk_fma_f32 v[68:69], v[72:73], v[66:67], v[84:85]
	v_pk_fma_f32 v[70:71], v[74:75], v[12:13], v[8:9]
	v_lshlrev_b32_e32 v72, 16, v10
	v_and_b32_e32 v73, 0xffff0000, v10
	v_lshlrev_b32_e32 v74, 16, v6
	v_and_b32_e32 v75, 0xffff0000, v6
	v_pk_mul_f32 v[76:77], v[58:59], v[76:77] op_sel_hi:[0,1]
	v_pk_mul_f32 v[18:19], v[56:57], v[18:19] op_sel_hi:[0,1]
	v_lshlrev_b32_e32 v10, 16, v11
	v_and_b32_e32 v11, 0xffff0000, v11
	v_lshlrev_b32_e32 v6, 16, v7
	v_and_b32_e32 v7, 0xffff0000, v7
	v_pk_mul_f32 v[14:15], v[58:59], v[14:15] op_sel_hi:[0,1]
	v_pk_mul_f32 v[72:73], v[60:61], v[72:73] op_sel_hi:[0,1]
	v_pk_mul_f32 v[74:75], v[54:55], v[74:75] op_sel_hi:[0,1]
	v_pk_mul_f32 v[76:77], v[16:17], v[76:77]
	v_pk_mul_f32 v[10:11], v[60:61], v[10:11] op_sel_hi:[0,1]
	v_pk_mul_f32 v[6:7], v[54:55], v[6:7] op_sel_hi:[0,1]
	v_pk_mul_f32 v[14:15], v[18:19], v[14:15]
	v_pk_mul_f32 v[72:73], v[72:73], v[16:17]
	v_pk_fma_f32 v[16:17], v[74:75], v[16:17], v[76:77]
	v_pk_mul_f32 v[10:11], v[10:11], v[18:19]
	v_pk_fma_f32 v[6:7], v[6:7], v[18:19], v[14:15]
	v_pk_fma_f32 v[74:75], v[16:17], 0.5, v[72:73] op_sel_hi:[1,0,1] neg_lo:[0,0,1] neg_hi:[0,0,1]
	v_pk_fma_f32 v[6:7], v[6:7], 0.5, v[10:11] op_sel_hi:[1,0,1] neg_lo:[0,0,1] neg_hi:[0,0,1]
	v_pk_fma_f32 v[16:17], v[24:25], v[74:75], v[72:73]
	v_pk_fma_f32 v[24:25], v[26:27], v[6:7], v[10:11]
	v_cvt_pk_bf16_f32 v16, v16, v17
	v_cvt_pk_bf16_f32 v17, v24, v25
	v_lshl_add_u64 v[24:25], s[6:7], 0, v[48:49]
	s_nop 0
	v_pk_fma_f32 v[18:19], v[6:7], v[30:31], v[10:11]
	v_add_co_u32_e32 v30, vcc, s2, v24
	s_mov_b32 s2, 0x5900000
	s_nop 0
	v_addc_co_u32_e32 v31, vcc, 0, v25, vcc
	s_nop 0
	v_pk_fma_f32 v[4:5], v[82:83], v[12:13], v[8:9]
	v_pk_fma_f32 v[8:9], v[78:79], v[12:13], v[8:9]
	v_pk_fma_f32 v[20:21], v[20:21], v[74:75], v[72:73]
	v_pk_fma_f32 v[22:23], v[22:23], v[6:7], v[10:11]
	v_cvt_pk_bf16_f32 v11, v12, v13
	v_cvt_pk_bf16_f32 v13, v6, v7
	v_cvt_pk_bf16_f32 v6, v62, v63
	v_add_co_u32_e32 v62, vcc, s2, v24
	v_pk_fma_f32 v[64:65], v[80:81], v[66:67], v[84:85]
	v_pk_fma_f32 v[28:29], v[74:75], v[28:29], v[72:73]
	v_cvt_pk_bf16_f32 v7, v8, v9
	v_cvt_pk_bf16_f32 v8, v20, v21
	v_cvt_pk_bf16_f32 v9, v22, v23
	v_addc_co_u32_e32 v63, vcc, 0, v25, vcc
	v_cvt_pk_bf16_f32 v14, v68, v69
	v_cvt_pk_bf16_f32 v15, v70, v71
	v_cvt_pk_bf16_f32 v10, v66, v67
	v_cvt_pk_bf16_f32 v12, v74, v75
	global_store_dwordx4 v[62:63], v[6:9], off
	global_store_dwordx4 v[30:31], v[14:17], off
	global_store_dwordx4 v[30:31], v[10:13], off offset:2048
	v_cvt_pk_bf16_f32 v6, v64, v65
	v_cvt_pk_bf16_f32 v7, v4, v5
	v_cvt_pk_bf16_f32 v8, v28, v29
	v_cvt_pk_bf16_f32 v9, v18, v19
	global_store_dwordx4 v[62:63], v[6:9], off offset:2048
	global_load_dwordx4 v[18:21], v[52:53], off
	v_mov_b32_e32 v4, 0
	v_mov_b32_e32 v5, 0
	s_and_saveexec_b64 s[12:13], s[36:37]
	s_cbranch_execz .LBB0_386
	global_load_dwordx4 v[2:5], v[52:53], off offset:-2048
